# latent attention finalize: lambda and sub-LN gains fetched up front, stores no longer drain
# speedup vs baseline: 1.0092x; 1.0092x over previous
.LBB0_874:
	v_readlane_b32 s2, v255, 43
	v_readlane_b32 s3, v255, 44
	s_mov_b32 s5, s59
	s_nop 0
	v_mov_b64_e32 v[2:3], s[2:3]
	flat_load_dword v1, v[2:3] sc0 sc1
	v_readlane_b32 s2, v255, 45
	v_readlane_b32 s3, v255, 46
	s_nop 1
	v_mov_b64_e32 v[84:85], s[2:3]
	flat_load_dword v4, v[84:85] sc0 sc1
	global_load_dwordx4 v[88:91], v210, s[34:35]
	global_load_dwordx4 v[92:95], v210, s[34:35] offset:32
	global_load_dwordx4 v[96:99], v210, s[34:35] offset:64
	global_load_dwordx4 v[100:103], v210, s[34:35] offset:96
	global_load_dwordx4 v[104:107], v210, s[34:35] offset:128
	global_load_dwordx4 v[108:111], v210, s[34:35] offset:160
	global_load_dwordx4 v[112:115], v210, s[34:35] offset:192
	global_load_dwordx4 v[116:119], v210, s[34:35] offset:224
	s_waitcnt vmcnt(0)
	ds_bpermute_b32 v2, v151, v167
	ds_bpermute_b32 v3, v151, v166
	s_waitcnt lgkmcnt(0)
	v_add_f32_e32 v2, v167, v2
	v_div_scale_f32 v5, s[2:3], v2, v2, 1.0
	v_rcp_f32_e32 v6, v5
	v_add_f32_e32 v3, v166, v3
	v_fma_f32 v7, -v5, v6, 1.0
	v_fmac_f32_e32 v6, v7, v6
	v_div_scale_f32 v7, vcc, 1.0, v2, 1.0
	v_mul_f32_e32 v8, v7, v6
	v_fma_f32 v9, -v5, v8, v7
	v_fmac_f32_e32 v8, v9, v6
	v_fma_f32 v5, -v5, v8, v7
	v_div_fmas_f32 v5, v5, v6, v8
	v_div_fixup_f32 v80, v5, v2, 1.0
	v_div_scale_f32 v2, s[2:3], v3, v3, v1
	v_rcp_f32_e32 v5, v2
	s_nop 0
	v_fma_f32 v6, -v2, v5, 1.0
	v_fmac_f32_e32 v5, v6, v5
	v_div_scale_f32 v6, vcc, v1, v3, v1
	v_mul_f32_e32 v7, v6, v5
	v_fma_f32 v8, -v2, v7, v6
	v_fmac_f32_e32 v7, v8, v5
	v_fma_f32 v2, -v2, v7, v6
	v_div_fmas_f32 v2, v2, v5, v7
	v_div_fixup_f32 v82, v2, v3, v1
	v_pk_mul_f32 v[2:3], v[60:61], v[82:83] op_sel_hi:[1,0]
	v_sub_f32_e32 v1, 1.0, v4
	v_pk_fma_f32 v[8:9], v[28:29], v[80:81], v[2:3] op_sel_hi:[1,0,1] neg_lo:[0,0,1] neg_hi:[0,0,1]
	v_pk_mul_f32 v[2:3], v[62:63], v[82:83] op_sel_hi:[1,0]
	v_pk_mul_f32 v[28:29], v[64:65], v[82:83] op_sel_hi:[1,0]
	v_pk_fma_f32 v[6:7], v[30:31], v[80:81], v[2:3] op_sel_hi:[1,0,1] neg_lo:[0,0,1] neg_hi:[0,0,1]
	v_lshlrev_b64 v[2:3], 11, v[148:149]
	v_lshl_add_u64 v[2:3], s[64:65], 0, v[2:3]
	v_lshl_add_u64 v[14:15], v[2:3], 0, s[4:5]
	v_pk_fma_f32 v[28:29], v[32:33], v[80:81], v[28:29] op_sel_hi:[1,0,1] neg_lo:[0,0,1] neg_hi:[0,0,1]
	v_pk_mul_f32 v[30:31], v[66:67], v[82:83] op_sel_hi:[1,0]
	v_pk_mul_f32 v[60:61], v[28:29], v[28:29]
	v_pk_fma_f32 v[30:31], v[34:35], v[80:81], v[30:31] op_sel_hi:[1,0,1] neg_lo:[0,0,1] neg_hi:[0,0,1]
	v_lshlrev_b32_e32 v32, 3, v150
	v_mov_b32_e32 v33, v211
	v_pk_mul_f32 v[62:63], v[30:31], v[30:31]
	v_lshl_add_u64 v[14:15], v[14:15], 0, v[32:33]
	v_pk_mul_f32 v[32:33], v[68:69], v[82:83] op_sel_hi:[1,0]
	v_add_f32_e32 v60, v60, v61
	v_pk_fma_f32 v[32:33], v[36:37], v[80:81], v[32:33] op_sel_hi:[1,0,1] neg_lo:[0,0,1] neg_hi:[0,0,1]
	v_add_f32_e32 v60, v62, v60
	v_pk_mul_f32 v[64:65], v[32:33], v[32:33]
	v_pk_mul_f32 v[34:35], v[70:71], v[82:83] op_sel_hi:[1,0]
	v_add_f32_e32 v60, v63, v60
	v_pk_fma_f32 v[34:35], v[38:39], v[80:81], v[34:35] op_sel_hi:[1,0,1] neg_lo:[0,0,1] neg_hi:[0,0,1]
	v_add_f32_e32 v60, v64, v60
	v_pk_mul_f32 v[66:67], v[34:35], v[34:35]
	v_pk_mul_f32 v[36:37], v[72:73], v[82:83] op_sel_hi:[1,0]
	v_add_f32_e32 v60, v65, v60
	v_pk_fma_f32 v[36:37], v[40:41], v[80:81], v[36:37] op_sel_hi:[1,0,1] neg_lo:[0,0,1] neg_hi:[0,0,1]
	v_add_f32_e32 v60, v66, v60
	v_pk_mul_f32 v[68:69], v[36:37], v[36:37]
	v_pk_mul_f32 v[38:39], v[74:75], v[82:83] op_sel_hi:[1,0]
	v_add_f32_e32 v60, v67, v60
	v_pk_fma_f32 v[38:39], v[42:43], v[80:81], v[38:39] op_sel_hi:[1,0,1] neg_lo:[0,0,1] neg_hi:[0,0,1]
	v_add_f32_e32 v60, v68, v60
	v_pk_mul_f32 v[70:71], v[38:39], v[38:39]
	v_pk_mul_f32 v[40:41], v[76:77], v[82:83] op_sel_hi:[1,0]
	v_add_f32_e32 v60, v69, v60
	v_pk_fma_f32 v[40:41], v[44:45], v[80:81], v[40:41] op_sel_hi:[1,0,1] neg_lo:[0,0,1] neg_hi:[0,0,1]
	v_add_f32_e32 v60, v70, v60
	v_pk_mul_f32 v[44:45], v[40:41], v[40:41]
	v_pk_mul_f32 v[42:43], v[78:79], v[82:83] op_sel_hi:[1,0]
	v_add_f32_e32 v60, v71, v60
	v_pk_fma_f32 v[42:43], v[46:47], v[80:81], v[42:43] op_sel_hi:[1,0,1] neg_lo:[0,0,1] neg_hi:[0,0,1]
	v_add_f32_e32 v44, v44, v60
	v_pk_mul_f32 v[46:47], v[42:43], v[42:43]
	v_pk_mul_f32 v[48:49], v[48:49], v[82:83] op_sel_hi:[1,0]
	v_add_f32_e32 v44, v45, v44
	v_pk_fma_f32 v[16:17], v[16:17], v[80:81], v[48:49] op_sel_hi:[1,0,1] neg_lo:[0,0,1] neg_hi:[0,0,1]
	v_add_f32_e32 v44, v46, v44
	v_pk_mul_f32 v[48:49], v[16:17], v[16:17]
	v_pk_mul_f32 v[50:51], v[50:51], v[82:83] op_sel_hi:[1,0]
	v_add_f32_e32 v44, v47, v44
	v_pk_fma_f32 v[18:19], v[18:19], v[80:81], v[50:51] op_sel_hi:[1,0,1] neg_lo:[0,0,1] neg_hi:[0,0,1]
	v_add_f32_e32 v44, v48, v44
	v_pk_mul_f32 v[50:51], v[18:19], v[18:19]
	v_pk_mul_f32 v[52:53], v[52:53], v[82:83] op_sel_hi:[1,0]
	v_add_f32_e32 v44, v49, v44
	v_pk_fma_f32 v[20:21], v[20:21], v[80:81], v[52:53] op_sel_hi:[1,0,1] neg_lo:[0,0,1] neg_hi:[0,0,1]
	v_add_f32_e32 v44, v50, v44
	v_pk_mul_f32 v[52:53], v[20:21], v[20:21]
	v_pk_mul_f32 v[54:55], v[54:55], v[82:83] op_sel_hi:[1,0]
	v_add_f32_e32 v44, v51, v44
	v_pk_fma_f32 v[22:23], v[22:23], v[80:81], v[54:55] op_sel_hi:[1,0,1] neg_lo:[0,0,1] neg_hi:[0,0,1]
	v_add_f32_e32 v44, v52, v44
	v_pk_mul_f32 v[54:55], v[22:23], v[22:23]
	v_pk_mul_f32 v[56:57], v[56:57], v[82:83] op_sel_hi:[1,0]
	v_add_f32_e32 v44, v53, v44
	v_pk_fma_f32 v[24:25], v[24:25], v[80:81], v[56:57] op_sel_hi:[1,0,1] neg_lo:[0,0,1] neg_hi:[0,0,1]
	v_add_f32_e32 v44, v54, v44
	v_pk_mul_f32 v[56:57], v[24:25], v[24:25]
	v_pk_mul_f32 v[58:59], v[58:59], v[82:83] op_sel_hi:[1,0]
	v_add_f32_e32 v44, v55, v44
	v_pk_fma_f32 v[26:27], v[26:27], v[80:81], v[58:59] op_sel_hi:[1,0,1] neg_lo:[0,0,1] neg_hi:[0,0,1]
	v_add_f32_e32 v44, v56, v44
	v_pk_mul_f32 v[58:59], v[26:27], v[26:27]
	v_add_f32_e32 v44, v57, v44
	v_add_f32_e32 v44, v58, v44
	v_pk_mul_f32 v[10:11], v[8:9], v[8:9]
	v_add_f32_e32 v44, v59, v44
	v_add_f32_e32 v10, v10, v44
	v_pk_mul_f32 v[12:13], v[6:7], v[6:7]
	v_add_f32_e32 v10, v11, v10
	v_add_f32_e32 v10, v12, v10
	v_add_f32_e32 v10, v13, v10
	ds_bpermute_b32 v11, v151, v10
	s_waitcnt lgkmcnt(0)
	v_add_f32_e32 v10, v10, v11
	v_fmamk_f32 v10, v10, 0x3c800000, v213
	v_cmp_gt_f32_e32 vcc, s38, v10
	v_mul_f32_e32 v11, 0x4b800000, v10
	s_nop 0
	v_cndmask_b32_e32 v10, v10, v11, vcc
	v_rsq_f32_e32 v10, v10
	s_nop 0
	v_mul_f32_e32 v11, 0x45800000, v10
	v_cndmask_b32_e32 v10, v10, v11, vcc
	v_mul_f32_e32 v10, v1, v10
	v_pk_mul_f32 v[12:13], v[28:29], v[10:11] op_sel_hi:[1,0]
	v_pk_mul_f32 v[8:9], v[8:9], v[10:11] op_sel_hi:[1,0]
	v_pk_mul_f32 v[2:3], v[88:89], v[12:13]
	v_pk_mul_f32 v[12:13], v[30:31], v[10:11] op_sel_hi:[1,0]
	v_cvt_pk_f16_f32 v2, v2, v3
	v_pk_mul_f32 v[4:5], v[90:91], v[12:13]
	v_pk_mul_f32 v[12:13], v[32:33], v[10:11] op_sel_hi:[1,0]
	v_cvt_pk_f16_f32 v3, v4, v5
	global_store_dwordx2 v[14:15], v[2:3], off offset:1536
	v_pk_mul_f32 v[6:7], v[6:7], v[10:11] op_sel_hi:[1,0]
	v_pk_mul_f32 v[2:3], v[92:93], v[12:13]
	v_pk_mul_f32 v[12:13], v[34:35], v[10:11] op_sel_hi:[1,0]
	v_cvt_pk_f16_f32 v2, v2, v3
	v_pk_mul_f32 v[4:5], v[94:95], v[12:13]
	v_pk_mul_f32 v[12:13], v[36:37], v[10:11] op_sel_hi:[1,0]
	v_cvt_pk_f16_f32 v3, v4, v5
	global_store_dwordx2 v[14:15], v[2:3], off offset:1552
	v_pk_mul_f32 v[2:3], v[96:97], v[12:13]
	v_pk_mul_f32 v[12:13], v[38:39], v[10:11] op_sel_hi:[1,0]
	v_cvt_pk_f16_f32 v2, v2, v3
	v_pk_mul_f32 v[4:5], v[98:99], v[12:13]
	v_pk_mul_f32 v[12:13], v[40:41], v[10:11] op_sel_hi:[1,0]
	v_cvt_pk_f16_f32 v3, v4, v5
	global_store_dwordx2 v[14:15], v[2:3], off offset:1568
	v_pk_mul_f32 v[2:3], v[100:101], v[12:13]
	v_pk_mul_f32 v[12:13], v[42:43], v[10:11] op_sel_hi:[1,0]
	v_cvt_pk_f16_f32 v2, v2, v3
	v_pk_mul_f32 v[4:5], v[102:103], v[12:13]
	v_pk_mul_f32 v[12:13], v[16:17], v[10:11] op_sel_hi:[1,0]
	v_cvt_pk_f16_f32 v3, v4, v5
	global_store_dwordx2 v[14:15], v[2:3], off offset:1584
	v_pk_mul_f32 v[2:3], v[104:105], v[12:13]
	v_pk_mul_f32 v[12:13], v[18:19], v[10:11] op_sel_hi:[1,0]
	v_cvt_pk_f16_f32 v2, v2, v3
	v_pk_mul_f32 v[4:5], v[106:107], v[12:13]
	v_pk_mul_f32 v[12:13], v[20:21], v[10:11] op_sel_hi:[1,0]
	v_cvt_pk_f16_f32 v3, v4, v5
	global_store_dwordx2 v[14:15], v[2:3], off offset:1600
	v_pk_mul_f32 v[2:3], v[108:109], v[12:13]
	v_pk_mul_f32 v[12:13], v[22:23], v[10:11] op_sel_hi:[1,0]
	v_cvt_pk_f16_f32 v2, v2, v3
	v_pk_mul_f32 v[4:5], v[110:111], v[12:13]
	v_pk_mul_f32 v[12:13], v[24:25], v[10:11] op_sel_hi:[1,0]
	v_cvt_pk_f16_f32 v3, v4, v5
	global_store_dwordx2 v[14:15], v[2:3], off offset:1616
	v_pk_mul_f32 v[2:3], v[112:113], v[12:13]
	v_pk_mul_f32 v[12:13], v[26:27], v[10:11] op_sel_hi:[1,0]
	v_cvt_pk_f16_f32 v2, v2, v3
	v_pk_mul_f32 v[4:5], v[114:115], v[12:13]
	s_nop 0
	v_cvt_pk_f16_f32 v3, v4, v5
	global_store_dwordx2 v[14:15], v[2:3], off offset:1632
	v_pk_mul_f32 v[2:3], v[116:117], v[8:9]
	v_pk_mul_f32 v[4:5], v[118:119], v[6:7]
	v_cvt_pk_f16_f32 v2, v2, v3
	v_cvt_pk_f16_f32 v3, v4, v5
	global_store_dwordx2 v[14:15], v[2:3], off offset:1648
